# GEMM K-loops at all four K=1024 sites: global loads and LDS writes issued inside MFMA gaps with recomputed lgkmcnt waits; inproj also saddr loads and 3 fragment sets
# speedup vs baseline: 1.0234x; 1.0144x over previous
; DI void gemm_ldg(const bf16_t* ga, const bf16_t* gb, int lda, int ldb, int koff, u32x4 (&ra)[4], u32x4 (&rb)[4]) {
; #pragma unroll
;   for (int i = 0; i < 4; ++i) {
;     ra[i] = *(const u32x4*)(ga + (size_t)(32 * i) * lda + koff);
;     rb[i] = *(const u32x4*)(gb + (size_t)(32 * i) * ldb + koff);
;   }
; }
; DI void gemm_sts(bf16_t* dA, bf16_t* dB, int r0, int c0, const u32x4 (&ra)[4], const u32x4 (&rb)[4]) {
; #pragma unroll
;   for (int i = 0; i < 4; ++i) {
;     *(u32x4*)(dA + (r0 + 32 * i) * LDT + c0 * 8) = ra[i];
;     *(u32x4*)(dB + (r0 + 32 * i) * LDT + c0 * 8) = rb[i];
;   }
; }
; DI void gemm_mma(const bf16_t* a_, const bf16_t* b_, f32x16 (&acc)[2][2]) {
;   __builtin_amdgcn_s_setprio(1);
; #pragma unroll
;   for (int kk = 0; kk < 4; ++kk) {
;     bf16x8 a0 = *(const bf16x8*)(a_ + kk * 16);
;     bf16x8 a1 = *(const bf16x8*)(a_ + 32 * LDT + kk * 16);
;     bf16x8 b0 = *(const bf16x8*)(b_ + kk * 16);
;     bf16x8 b1 = *(const bf16x8*)(b_ + 32 * LDT + kk * 16);
;     acc[0][0] = MFMA(a0, b0, acc[0][0]);
;     acc[0][1] = MFMA(a0, b1, acc[0][1]);
;     acc[1][0] = MFMA(a1, b0, acc[1][0]);
;     acc[1][1] = MFMA(a1, b1, acc[1][1]);
;   }
;   __builtin_amdgcn_s_setprio(0);
; }
; DI void gemm_tile(const bf16_t* __restrict__ A, int lda, const bf16_t* __restrict__ B, int ldb, int K,
;                   f32x16 (&acc)[2][2], char* smem) {
;   const int tid = threadIdx.x, lane = tid & 63, w = tid >> 6, wm = w >> 1, wn = w & 1;
;   bf16_t* sA = (bf16_t*)smem;
;   bf16_t* sB = sA + 2 * 128 * LDT;
;   const int r0 = tid >> 3, c0 = tid & 7;
;   const bf16_t* ga = A + (size_t)r0 * lda + c0 * 8;
;   const bf16_t* gb = B + (size_t)r0 * ldb + c0 * 8;
;   const int aoff = (wm * 64 + (lane & 31)) * LDT + (lane >> 5) * 8;
;   const int boff = (wn * 64 + (lane & 31)) * LDT + (lane >> 5) * 8;
;   u32x4 ra0[4], rb0[4], ra1[4], rb1[4];
;   gemm_ldg(ga, gb, lda, ldb, 0, ra0, rb0);
;   gemm_ldg(ga, gb, lda, ldb, 64, ra1, rb1);
;   __syncthreads();
;   gemm_sts(sA, sB, r0, c0, ra0, rb0);
;   __syncthreads();
;   const int nk = K >> 6;
; #pragma unroll 1
;   for (int kt = 0; kt < nk; kt += 2) {
;     if (kt + 2 < nk) gemm_ldg(ga, gb, lda, ldb, (kt + 2) * 64, ra0, rb0);
;     gemm_mma(sA + aoff, sB + boff, acc);
;     gemm_sts(sA + 128 * LDT, sB + 128 * LDT, r0, c0, ra1, rb1);
;     __syncthreads();
;     if (kt + 3 < nk) gemm_ldg(ga, gb, lda, ldb, (kt + 3) * 64, ra1, rb1);
.Lfast1_top:
	ds_read_b128 v[166:169], v156
	ds_read_b128 v[170:173], v157 offset:36864
	ds_read_b128 v[174:177], v157 offset:41472
	ds_read_b128 v[178:181], v156 offset:4608
	ds_read_b128 v[182:185], v156 offset:32
	ds_read_b128 v[186:189], v157 offset:36896
	ds_read_b128 v[190:193], v157 offset:41504
	ds_read_b128 v[194:197], v156 offset:4640
	s_setprio 1
	s_waitcnt lgkmcnt(6)
	v_mfma_f32_32x32x16_bf16 v[50:65], v[166:169], v[170:173], v[50:65]
	ds_read_b128 v[198:201], v156 offset:64
	global_load_dwordx4 v[66:69], v216, s[84:85] offset:256
	s_waitcnt lgkmcnt(6)
	v_mfma_f32_32x32x16_bf16 v[34:49], v[166:169], v[174:177], v[34:49]
	ds_read_b128 v[202:205], v157 offset:36928
	global_load_dwordx4 v[70:73], v217, s[84:85] offset:256
	s_waitcnt lgkmcnt(6)
	v_mfma_f32_32x32x16_bf16 v[18:33], v[178:181], v[170:173], v[18:33]
	ds_read_b128 v[206:209], v157 offset:41536
	global_load_dwordx4 v[74:77], v217, s[86:87] offset:256
	v_mfma_f32_32x32x16_bf16 v[2:17], v[178:181], v[174:177], v[2:17]
	ds_read_b128 v[210:213], v156 offset:4672
	global_load_dwordx4 v[78:81], v218, s[84:85] offset:256
	s_waitcnt lgkmcnt(6)
	v_mfma_f32_32x32x16_bf16 v[50:65], v[182:185], v[186:189], v[50:65]
	ds_read_b128 v[166:169], v156 offset:96
	global_load_dwordx4 v[82:85], v218, s[86:87] offset:256
	s_waitcnt lgkmcnt(6)
	v_mfma_f32_32x32x16_bf16 v[34:49], v[182:185], v[190:193], v[34:49]
	ds_read_b128 v[170:173], v157 offset:36960
	global_load_dwordx4 v[86:89], v219, s[84:85] offset:256
	s_waitcnt lgkmcnt(6)
	v_mfma_f32_32x32x16_bf16 v[18:33], v[194:197], v[186:189], v[18:33]
	ds_read_b128 v[174:177], v157 offset:41568
	global_load_dwordx4 v[90:93], v216, s[86:87] offset:256
	v_mfma_f32_32x32x16_bf16 v[2:17], v[194:197], v[190:193], v[2:17]
	ds_read_b128 v[178:181], v156 offset:4704
	global_load_dwordx4 v[102:105], v219, s[86:87] offset:256
	s_waitcnt lgkmcnt(6)
	v_mfma_f32_32x32x16_bf16 v[50:65], v[198:201], v[202:205], v[50:65]
	s_waitcnt vmcnt(8)
	ds_write_b128 v1, v[94:97] offset:18432
	s_waitcnt lgkmcnt(6)
	v_mfma_f32_32x32x16_bf16 v[34:49], v[198:201], v[206:209], v[34:49]
	ds_write_b128 v1, v[122:125] offset:55296
	s_waitcnt lgkmcnt(6)
	v_mfma_f32_32x32x16_bf16 v[18:33], v[210:213], v[202:205], v[18:33]
	ds_write_b128 v1, v[98:101] offset:23040
	v_mfma_f32_32x32x16_bf16 v[2:17], v[210:213], v[206:209], v[2:17]
	ds_write_b128 v1, v[106:109] offset:59904
	s_waitcnt lgkmcnt(6)
	v_mfma_f32_32x32x16_bf16 v[50:65], v[166:169], v[170:173], v[50:65]
	ds_write_b128 v1, v[110:113] offset:27648
	s_waitcnt lgkmcnt(6)
	v_mfma_f32_32x32x16_bf16 v[34:49], v[166:169], v[174:177], v[34:49]
	ds_write_b128 v1, v[114:117] offset:64512
	s_waitcnt lgkmcnt(6)
	v_mfma_f32_32x32x16_bf16 v[18:33], v[178:181], v[170:173], v[18:33]
	ds_write_b128 v1, v[118:121] offset:32256
	v_mfma_f32_32x32x16_bf16 v[2:17], v[178:181], v[174:177], v[2:17]
	ds_write_b128 v158, v[126:129] offset:13824
	s_setprio 0
	s_waitcnt lgkmcnt(0)
	s_barrier
	ds_read_b128 v[166:169], v156 offset:18432
	ds_read_b128 v[170:173], v157 offset:55296
	ds_read_b128 v[174:177], v157 offset:59904
	ds_read_b128 v[178:181], v156 offset:23040
	ds_read_b128 v[182:185], v156 offset:18464
	ds_read_b128 v[186:189], v157 offset:55328
	ds_read_b128 v[190:193], v157 offset:59936
	ds_read_b128 v[194:197], v156 offset:23072
	s_setprio 1
	s_waitcnt lgkmcnt(6)
	v_mfma_f32_32x32x16_bf16 v[50:65], v[166:169], v[170:173], v[50:65]
	ds_read_b128 v[198:201], v156 offset:18496
	global_load_dwordx4 v[94:97], v216, s[84:85] offset:384
	s_waitcnt lgkmcnt(6)
	v_mfma_f32_32x32x16_bf16 v[34:49], v[166:169], v[174:177], v[34:49]
	ds_read_b128 v[202:205], v157 offset:55360
	global_load_dwordx4 v[98:101], v217, s[84:85] offset:384
	s_waitcnt lgkmcnt(6)
	v_mfma_f32_32x32x16_bf16 v[18:33], v[178:181], v[170:173], v[18:33]
	ds_read_b128 v[206:209], v157 offset:59968
	global_load_dwordx4 v[106:109], v217, s[86:87] offset:384
	v_mfma_f32_32x32x16_bf16 v[2:17], v[178:181], v[174:177], v[2:17]
	ds_read_b128 v[210:213], v156 offset:23104
	global_load_dwordx4 v[110:113], v218, s[84:85] offset:384
	s_waitcnt lgkmcnt(6)
	v_mfma_f32_32x32x16_bf16 v[50:65], v[182:185], v[186:189], v[50:65]
	ds_read_b128 v[166:169], v156 offset:18528
	global_load_dwordx4 v[114:117], v218, s[86:87] offset:384
	s_waitcnt lgkmcnt(6)
	v_mfma_f32_32x32x16_bf16 v[34:49], v[182:185], v[190:193], v[34:49]
	ds_read_b128 v[170:173], v157 offset:55392
	global_load_dwordx4 v[118:121], v219, s[84:85] offset:384
	s_waitcnt lgkmcnt(6)
	v_mfma_f32_32x32x16_bf16 v[18:33], v[194:197], v[186:189], v[18:33]
	ds_read_b128 v[174:177], v157 offset:60000
	global_load_dwordx4 v[122:125], v216, s[86:87] offset:384
	v_mfma_f32_32x32x16_bf16 v[2:17], v[194:197], v[190:193], v[2:17]
	ds_read_b128 v[178:181], v156 offset:23136
	global_load_dwordx4 v[126:129], v219, s[86:87] offset:384
	s_waitcnt lgkmcnt(6)
	v_mfma_f32_32x32x16_bf16 v[50:65], v[198:201], v[202:205], v[50:65]
	s_waitcnt vmcnt(8)
	ds_write_b128 v1, v[66:69]
	s_waitcnt lgkmcnt(6)
	v_mfma_f32_32x32x16_bf16 v[34:49], v[198:201], v[206:209], v[34:49]
	ds_write_b128 v1, v[90:93] offset:36864
	s_waitcnt lgkmcnt(6)
	v_mfma_f32_32x32x16_bf16 v[18:33], v[210:213], v[202:205], v[18:33]
	ds_write_b128 v1, v[70:73] offset:4608
	v_mfma_f32_32x32x16_bf16 v[2:17], v[210:213], v[206:209], v[2:17]
	ds_write_b128 v1, v[74:77] offset:41472
	s_waitcnt lgkmcnt(6)
	v_mfma_f32_32x32x16_bf16 v[50:65], v[166:169], v[170:173], v[50:65]
	ds_write_b128 v1, v[78:81] offset:9216
	s_waitcnt lgkmcnt(6)
	v_mfma_f32_32x32x16_bf16 v[34:49], v[166:169], v[174:177], v[34:49]
	ds_write_b128 v1, v[82:85] offset:46080
	s_waitcnt lgkmcnt(6)
	v_mfma_f32_32x32x16_bf16 v[18:33], v[178:181], v[170:173], v[18:33]
	ds_write_b128 v1, v[86:89] offset:13824
	v_mfma_f32_32x32x16_bf16 v[2:17], v[178:181], v[174:177], v[2:17]
	ds_write_b128 v1, v[102:105] offset:50688
	s_setprio 0
	s_add_i32 s8, s8, 2
	s_add_u32 s84, s84, 0x100
	s_addc_u32 s85, s85, 0
	s_add_u32 s86, s86, 0x100
	s_addc_u32 s87, s87, 0
	s_waitcnt lgkmcnt(0)
	s_barrier
	s_cmp_lt_u32 s8, 14
	s_cbranch_scc1 .Lfast1_top
	s_branch .LBB0_102

; DI void gemm_ldg(const bf16_t* ga, const bf16_t* gb, int lda, int ldb, int koff, u32x4 (&ra)[4], u32x4 (&rb)[4]) {
; #pragma unroll
;   for (int i = 0; i < 4; ++i) {
;     ra[i] = *(const u32x4*)(ga + (size_t)(32 * i) * lda + koff);
;     rb[i] = *(const u32x4*)(gb + (size_t)(32 * i) * ldb + koff);
;   }
; }
; DI void gemm_sts(bf16_t* dA, bf16_t* dB, int r0, int c0, const u32x4 (&ra)[4], const u32x4 (&rb)[4]) {
; #pragma unroll
;   for (int i = 0; i < 4; ++i) {
;     *(u32x4*)(dA + (r0 + 32 * i) * LDT + c0 * 8) = ra[i];
;     *(u32x4*)(dB + (r0 + 32 * i) * LDT + c0 * 8) = rb[i];
;   }
; }
; DI void gemm_mma(const bf16_t* a_, const bf16_t* b_, f32x16 (&acc)[2][2]) {
;   __builtin_amdgcn_s_setprio(1);
; #pragma unroll
;   for (int kk = 0; kk < 4; ++kk) {
;     bf16x8 a0 = *(const bf16x8*)(a_ + kk * 16);
;     bf16x8 a1 = *(const bf16x8*)(a_ + 32 * LDT + kk * 16);
;     bf16x8 b0 = *(const bf16x8*)(b_ + kk * 16);
;     bf16x8 b1 = *(const bf16x8*)(b_ + 32 * LDT + kk * 16);
;     acc[0][0] = MFMA(a0, b0, acc[0][0]);
;     acc[0][1] = MFMA(a0, b1, acc[0][1]);
;     acc[1][0] = MFMA(a1, b0, acc[1][0]);
;     acc[1][1] = MFMA(a1, b1, acc[1][1]);
;   }
;   __builtin_amdgcn_s_setprio(0);
; }
; DI void gemm_tile(const bf16_t* __restrict__ A, int lda, const bf16_t* __restrict__ B, int ldb, int K,
;                   f32x16 (&acc)[2][2], char* smem) {
;   const int tid = threadIdx.x, lane = tid & 63, w = tid >> 6, wm = w >> 1, wn = w & 1;
;   bf16_t* sA = (bf16_t*)smem;
;   bf16_t* sB = sA + 2 * 128 * LDT;
;   const int r0 = tid >> 3, c0 = tid & 7;
;   const bf16_t* ga = A + (size_t)r0 * lda + c0 * 8;
;   const bf16_t* gb = B + (size_t)r0 * ldb + c0 * 8;
;   const int aoff = (wm * 64 + (lane & 31)) * LDT + (lane >> 5) * 8;
;   const int boff = (wn * 64 + (lane & 31)) * LDT + (lane >> 5) * 8;
;   u32x4 ra0[4], rb0[4], ra1[4], rb1[4];
;   gemm_ldg(ga, gb, lda, ldb, 0, ra0, rb0);
;   gemm_ldg(ga, gb, lda, ldb, 64, ra1, rb1);
;   __syncthreads();
;   gemm_sts(sA, sB, r0, c0, ra0, rb0);
;   __syncthreads();
;   const int nk = K >> 6;
; #pragma unroll 1
;   for (int kt = 0; kt < nk; kt += 2) {
;     if (kt + 2 < nk) gemm_ldg(ga, gb, lda, ldb, (kt + 2) * 64, ra0, rb0);
;     gemm_mma(sA + aoff, sB + boff, acc);
;     gemm_sts(sA + 128 * LDT, sB + 128 * LDT, r0, c0, ra1, rb1);
;     __syncthreads();
;     if (kt + 3 < nk) gemm_ldg(ga, gb, lda, ldb, (kt + 3) * 64, ra1, rb1);
.Lgf2_top:
	s_add_i32 s44, s44, 2
	s_cmp_lt_u32 s44, 14
	s_cselect_b64 s[42:43], -1, 0
	s_cmp_gt_u32 s44, 13
	s_cselect_b64 s[40:41], -1, 0
	s_and_b64 vcc, exec, s[40:41]
	v_lshl_add_u64 v[222:223], s[34:35], 0, v[160:161]
	v_lshl_add_u64 v[220:221], v[218:219], 0, v[158:159]
	s_setprio 1
	ds_read_b128 v[240:243], v231
	ds_read_b128 v[244:247], v232 offset:36864
	ds_read_b128 v[248:251], v232 offset:41472
	s_waitcnt lgkmcnt(1)
	v_mfma_f32_32x32x16_bf16 v[50:65], v[240:243], v[244:247], v[50:65]
	v_add_co_u32_e32 v66, vcc, 0x5300000, v222
	s_nop 1
	v_addc_co_u32_e32 v67, vcc, 0, v223, vcc
	v_add_co_u32_e32 v70, vcc, 0x680000, v220
	global_load_dwordx4 v[66:69], v[66:67], off offset:256
	s_waitcnt lgkmcnt(0)
	v_mfma_f32_32x32x16_bf16 v[34:49], v[240:243], v[248:251], v[34:49]
	s_nop 0
	v_addc_co_u32_e32 v71, vcc, 0, v221, vcc
	v_add_co_u32_e32 v74, vcc, 0x5310000, v222
	global_load_dwordx4 v[70:73], v[70:71], off offset:256
	ds_read_b128 v[240:243], v231 offset:4608
	s_waitcnt lgkmcnt(0)
	v_mfma_f32_32x32x16_bf16 v[18:33], v[240:243], v[244:247], v[18:33]
	s_nop 0
	v_addc_co_u32_e32 v75, vcc, 0, v223, vcc
	v_add_co_u32_e32 v82, vcc, 0x690000, v220
	global_load_dwordx4 v[74:77], v[74:75], off offset:256
	s_waitcnt lgkmcnt(0)
	v_mfma_f32_32x32x16_bf16 v[2:17], v[240:243], v[248:251], v[2:17]
	s_nop 0
	v_addc_co_u32_e32 v83, vcc, 0, v221, vcc
	v_add_co_u32_e32 v86, vcc, 0x5320000, v222
	global_load_dwordx4 v[82:85], v[82:83], off offset:256
	ds_read_b128 v[240:243], v231 offset:32
	ds_read_b128 v[244:247], v232 offset:36896
	ds_read_b128 v[248:251], v232 offset:41504
	s_waitcnt lgkmcnt(1)
	v_mfma_f32_32x32x16_bf16 v[50:65], v[240:243], v[244:247], v[50:65]
	s_nop 0
	v_addc_co_u32_e32 v87, vcc, 0, v223, vcc
	v_add_co_u32_e32 v94, vcc, 0x6a0000, v220
	global_load_dwordx4 v[86:89], v[86:87], off offset:256
	s_waitcnt lgkmcnt(0)
	v_mfma_f32_32x32x16_bf16 v[34:49], v[240:243], v[248:251], v[34:49]
	s_nop 0
	v_addc_co_u32_e32 v95, vcc, 0, v221, vcc
	v_add_co_u32_e32 v102, vcc, 0x5330000, v222
	global_load_dwordx4 v[94:97], v[94:95], off offset:256
	ds_read_b128 v[240:243], v231 offset:4640
	s_waitcnt lgkmcnt(0)
	v_mfma_f32_32x32x16_bf16 v[18:33], v[240:243], v[244:247], v[18:33]
	s_nop 0
	v_addc_co_u32_e32 v103, vcc, 0, v223, vcc
	v_add_co_u32_e32 v110, vcc, s64, v220
	global_load_dwordx4 v[102:105], v[102:103], off offset:256
	s_waitcnt lgkmcnt(0)
	v_mfma_f32_32x32x16_bf16 v[2:17], v[240:243], v[248:251], v[2:17]
	s_nop 0
	v_addc_co_u32_e32 v111, vcc, 0, v221, vcc
	global_load_dwordx4 v[110:113], v[110:111], off offset:256
	ds_read_b128 v[240:243], v231 offset:64
	ds_read_b128 v[244:247], v232 offset:36928
	ds_read_b128 v[248:251], v232 offset:41536
	s_waitcnt lgkmcnt(1)
	v_mfma_f32_32x32x16_bf16 v[50:65], v[240:243], v[244:247], v[50:65]
	s_waitcnt vmcnt(8)
	ds_write_b128 v230, v[78:81] offset:18432
	s_waitcnt lgkmcnt(1)
	v_mfma_f32_32x32x16_bf16 v[34:49], v[240:243], v[248:251], v[34:49]
	ds_write_b128 v230, v[114:117] offset:55296
	ds_read_b128 v[240:243], v231 offset:4672
	s_waitcnt lgkmcnt(0)
	v_mfma_f32_32x32x16_bf16 v[18:33], v[240:243], v[244:247], v[18:33]
	ds_write_b128 v230, v[90:93] offset:23040
	s_waitcnt lgkmcnt(1)
	v_mfma_f32_32x32x16_bf16 v[2:17], v[240:243], v[248:251], v[2:17]
	ds_write_b128 v230, v[118:121] offset:59904
	ds_read_b128 v[240:243], v231 offset:96
	ds_read_b128 v[244:247], v232 offset:36960
	ds_read_b128 v[248:251], v232 offset:41568
	s_waitcnt lgkmcnt(1)
	v_mfma_f32_32x32x16_bf16 v[50:65], v[240:243], v[244:247], v[50:65]
	ds_write_b128 v230, v[98:101] offset:27648
	s_waitcnt lgkmcnt(1)
	v_mfma_f32_32x32x16_bf16 v[34:49], v[240:243], v[248:251], v[34:49]
	ds_write_b128 v230, v[122:125] offset:64512
	ds_read_b128 v[240:243], v231 offset:4704
	s_waitcnt lgkmcnt(0)
	v_mfma_f32_32x32x16_bf16 v[18:33], v[240:243], v[244:247], v[18:33]
	ds_write_b128 v230, v[106:109] offset:32256
	s_waitcnt lgkmcnt(1)
	v_mfma_f32_32x32x16_bf16 v[2:17], v[240:243], v[248:251], v[2:17]
	ds_write_b128 v233, v[126:129] offset:13824
	s_setprio 0
	s_waitcnt lgkmcnt(0)
	s_barrier
; DI void gemm_ldg(const bf16_t* ga, const bf16_t* gb, int lda, int ldb, int koff, u32x4 (&ra)[4], u32x4 (&rb)[4]) {
; #pragma unroll
;   for (int i = 0; i < 4; ++i) {
;     ra[i] = *(const u32x4*)(ga + (size_t)(32 * i) * lda + koff);
;     rb[i] = *(const u32x4*)(gb + (size_t)(32 * i) * ldb + koff);
;   }
; }
; DI void gemm_sts(bf16_t* dA, bf16_t* dB, int r0, int c0, const u32x4 (&ra)[4], const u32x4 (&rb)[4]) {
; #pragma unroll
;   for (int i = 0; i < 4; ++i) {
;     *(u32x4*)(dA + (r0 + 32 * i) * LDT + c0 * 8) = ra[i];
;     *(u32x4*)(dB + (r0 + 32 * i) * LDT + c0 * 8) = rb[i];
;   }
; }
; DI void gemm_mma(const bf16_t* a_, const bf16_t* b_, f32x16 (&acc)[2][2]) {
;   __builtin_amdgcn_s_setprio(1);
; #pragma unroll
;   for (int kk = 0; kk < 4; ++kk) {
;     bf16x8 a0 = *(const bf16x8*)(a_ + kk * 16);
;     bf16x8 a1 = *(const bf16x8*)(a_ + 32 * LDT + kk * 16);
;     bf16x8 b0 = *(const bf16x8*)(b_ + kk * 16);
;     bf16x8 b1 = *(const bf16x8*)(b_ + 32 * LDT + kk * 16);
;     acc[0][0] = MFMA(a0, b0, acc[0][0]);
;     acc[0][1] = MFMA(a0, b1, acc[0][1]);
;     acc[1][0] = MFMA(a1, b0, acc[1][0]);
;     acc[1][1] = MFMA(a1, b1, acc[1][1]);
;   }
;   __builtin_amdgcn_s_setprio(0);
; }
; DI void gemm_tile(const bf16_t* __restrict__ A, int lda, const bf16_t* __restrict__ B, int ldb, int K,
;                   f32x16 (&acc)[2][2], char* smem) {
;   const int tid = threadIdx.x, lane = tid & 63, w = tid >> 6, wm = w >> 1, wn = w & 1;
;   bf16_t* sA = (bf16_t*)smem;
;   bf16_t* sB = sA + 2 * 128 * LDT;
;   const int r0 = tid >> 3, c0 = tid & 7;
;   const bf16_t* ga = A + (size_t)r0 * lda + c0 * 8;
;   const bf16_t* gb = B + (size_t)r0 * ldb + c0 * 8;
;   const int aoff = (wm * 64 + (lane & 31)) * LDT + (lane >> 5) * 8;
;   const int boff = (wn * 64 + (lane & 31)) * LDT + (lane >> 5) * 8;
;   u32x4 ra0[4], rb0[4], ra1[4], rb1[4];
;   gemm_ldg(ga, gb, lda, ldb, 0, ra0, rb0);
;   gemm_ldg(ga, gb, lda, ldb, 64, ra1, rb1);
;   __syncthreads();
;   gemm_sts(sA, sB, r0, c0, ra0, rb0);
;   __syncthreads();
;   const int nk = K >> 6;
; #pragma unroll 1
;   for (int kt = 0; kt < nk; kt += 2) {
;     if (kt + 2 < nk) gemm_ldg(ga, gb, lda, ldb, (kt + 2) * 64, ra0, rb0);
;     gemm_mma(sA + aoff, sB + boff, acc);
;     gemm_sts(sA + 128 * LDT, sB + 128 * LDT, r0, c0, ra1, rb1);
;     __syncthreads();
;     if (kt + 3 < nk) gemm_ldg(ga, gb, lda, ldb, (kt + 3) * 64, ra1, rb1);
	s_setprio 1
	ds_read_b128 v[252:255], v231 offset:18432
	ds_read_b128 v[240:243], v232 offset:55296
	ds_read_b128 v[244:247], v232 offset:59904
	s_waitcnt lgkmcnt(1)
	v_mfma_f32_32x32x16_bf16 v[50:65], v[252:255], v[240:243], v[50:65]
	v_add_co_u32_e32 v78, vcc, 0x5300000, v222
	s_nop 1
	v_addc_co_u32_e32 v79, vcc, 0, v223, vcc
	v_add_co_u32_e32 v90, vcc, 0x680000, v220
	global_load_dwordx4 v[78:81], v[78:79], off offset:384
	s_waitcnt lgkmcnt(0)
	v_mfma_f32_32x32x16_bf16 v[34:49], v[252:255], v[244:247], v[34:49]
	s_nop 0
	v_addc_co_u32_e32 v91, vcc, 0, v221, vcc
	global_load_dwordx4 v[114:117], v[90:91], off offset:384
	ds_read_b128 v[252:255], v231 offset:23040
	s_waitcnt lgkmcnt(0)
	v_mfma_f32_32x32x16_bf16 v[18:33], v[252:255], v[240:243], v[18:33]
	v_add_co_u32_e32 v90, vcc, 0x5310000, v222
	s_nop 1
	v_addc_co_u32_e32 v91, vcc, 0, v223, vcc
	v_add_co_u32_e32 v98, vcc, 0x690000, v220
	global_load_dwordx4 v[90:93], v[90:91], off offset:384
	s_waitcnt lgkmcnt(0)
	v_mfma_f32_32x32x16_bf16 v[2:17], v[252:255], v[244:247], v[2:17]
	s_nop 0
	v_addc_co_u32_e32 v99, vcc, 0, v221, vcc
	global_load_dwordx4 v[118:121], v[98:99], off offset:384
	ds_read_b128 v[252:255], v231 offset:18464
	ds_read_b128 v[240:243], v232 offset:55328
	ds_read_b128 v[244:247], v232 offset:59936
	s_waitcnt lgkmcnt(1)
	v_mfma_f32_32x32x16_bf16 v[50:65], v[252:255], v[240:243], v[50:65]
	v_add_co_u32_e32 v98, vcc, 0x5320000, v222
	s_nop 1
	v_addc_co_u32_e32 v99, vcc, 0, v223, vcc
	v_add_co_u32_e32 v106, vcc, 0x6a0000, v220
	global_load_dwordx4 v[98:101], v[98:99], off offset:384
	s_waitcnt lgkmcnt(0)
	v_mfma_f32_32x32x16_bf16 v[34:49], v[252:255], v[244:247], v[34:49]
	s_nop 0
	v_addc_co_u32_e32 v107, vcc, 0, v221, vcc
	global_load_dwordx4 v[122:125], v[106:107], off offset:384
	ds_read_b128 v[252:255], v231 offset:23072
	s_waitcnt lgkmcnt(0)
	v_mfma_f32_32x32x16_bf16 v[18:33], v[252:255], v[240:243], v[18:33]
	v_add_co_u32_e32 v106, vcc, 0x5330000, v222
	s_nop 1
	v_addc_co_u32_e32 v107, vcc, 0, v223, vcc
	v_add_co_u32_e32 v126, vcc, 0x6b0000, v220
	global_load_dwordx4 v[106:109], v[106:107], off offset:384
	s_waitcnt lgkmcnt(0)
	v_mfma_f32_32x32x16_bf16 v[2:17], v[252:255], v[244:247], v[2:17]
	s_nop 0
	v_addc_co_u32_e32 v127, vcc, 0, v221, vcc
	global_load_dwordx4 v[126:129], v[126:127], off offset:384
	ds_read_b128 v[252:255], v231 offset:18496
	ds_read_b128 v[240:243], v232 offset:55360
	ds_read_b128 v[244:247], v232 offset:59968
	s_waitcnt lgkmcnt(1)
	v_mfma_f32_32x32x16_bf16 v[50:65], v[252:255], v[240:243], v[50:65]
	s_waitcnt vmcnt(8)
	ds_write_b128 v230, v[66:69]
	s_waitcnt lgkmcnt(1)
	v_mfma_f32_32x32x16_bf16 v[34:49], v[252:255], v[244:247], v[34:49]
	ds_write_b128 v230, v[70:73] offset:36864
	ds_read_b128 v[252:255], v231 offset:23104
	s_waitcnt lgkmcnt(0)
	v_mfma_f32_32x32x16_bf16 v[18:33], v[252:255], v[240:243], v[18:33]
	ds_write_b128 v230, v[74:77] offset:4608
	s_waitcnt lgkmcnt(1)
	v_mfma_f32_32x32x16_bf16 v[2:17], v[252:255], v[244:247], v[2:17]
	ds_write_b128 v230, v[82:85] offset:41472
	ds_read_b128 v[252:255], v231 offset:18528
	ds_read_b128 v[240:243], v232 offset:55392
	ds_read_b128 v[244:247], v232 offset:60000
	s_waitcnt lgkmcnt(1)
	v_mfma_f32_32x32x16_bf16 v[50:65], v[252:255], v[240:243], v[50:65]
	ds_write_b128 v230, v[86:89] offset:9216
	s_waitcnt lgkmcnt(1)
	v_mfma_f32_32x32x16_bf16 v[34:49], v[252:255], v[244:247], v[34:49]
	ds_write_b128 v230, v[94:97] offset:46080
	ds_read_b128 v[252:255], v231 offset:23136
	s_waitcnt lgkmcnt(0)
	v_mfma_f32_32x32x16_bf16 v[18:33], v[252:255], v[240:243], v[18:33]
	ds_write_b128 v230, v[102:105] offset:13824
	s_waitcnt lgkmcnt(1)
	v_mfma_f32_32x32x16_bf16 v[2:17], v[252:255], v[244:247], v[2:17]
	ds_write_b128 v230, v[110:113] offset:50688
	s_setprio 0
	s_add_u32 s34, s34, 0x100
	s_addc_u32 s35, s35, 0
	s_andn2_b64 vcc, exec, s[40:41]
	v_lshl_add_u64 v[218:219], v[218:219], 0, s[24:25]
	s_waitcnt lgkmcnt(0)
	s_barrier
	s_cmp_lt_u32 s44, 12
	s_cbranch_scc1 .Lgf2_top
	s_branch .LBB0_288

; DI void gemm_ldg(const bf16_t* ga, const bf16_t* gb, int lda, int ldb, int koff, u32x4 (&ra)[4], u32x4 (&rb)[4]) {
; #pragma unroll
;   for (int i = 0; i < 4; ++i) {
;     ra[i] = *(const u32x4*)(ga + (size_t)(32 * i) * lda + koff);
;     rb[i] = *(const u32x4*)(gb + (size_t)(32 * i) * ldb + koff);
;   }
; }
; DI void gemm_sts(bf16_t* dA, bf16_t* dB, int r0, int c0, const u32x4 (&ra)[4], const u32x4 (&rb)[4]) {
; #pragma unroll
;   for (int i = 0; i < 4; ++i) {
;     *(u32x4*)(dA + (r0 + 32 * i) * LDT + c0 * 8) = ra[i];
;     *(u32x4*)(dB + (r0 + 32 * i) * LDT + c0 * 8) = rb[i];
;   }
; }
; DI void gemm_mma(const bf16_t* a_, const bf16_t* b_, f32x16 (&acc)[2][2]) {
;   __builtin_amdgcn_s_setprio(1);
; #pragma unroll
;   for (int kk = 0; kk < 4; ++kk) {
;     bf16x8 a0 = *(const bf16x8*)(a_ + kk * 16);
;     bf16x8 a1 = *(const bf16x8*)(a_ + 32 * LDT + kk * 16);
;     bf16x8 b0 = *(const bf16x8*)(b_ + kk * 16);
;     bf16x8 b1 = *(const bf16x8*)(b_ + 32 * LDT + kk * 16);
;     acc[0][0] = MFMA(a0, b0, acc[0][0]);
;     acc[0][1] = MFMA(a0, b1, acc[0][1]);
;     acc[1][0] = MFMA(a1, b0, acc[1][0]);
;     acc[1][1] = MFMA(a1, b1, acc[1][1]);
;   }
;   __builtin_amdgcn_s_setprio(0);
; }
; DI void gemm_tile(const bf16_t* __restrict__ A, int lda, const bf16_t* __restrict__ B, int ldb, int K,
;                   f32x16 (&acc)[2][2], char* smem) {
;   const int tid = threadIdx.x, lane = tid & 63, w = tid >> 6, wm = w >> 1, wn = w & 1;
;   bf16_t* sA = (bf16_t*)smem;
;   bf16_t* sB = sA + 2 * 128 * LDT;
;   const int r0 = tid >> 3, c0 = tid & 7;
;   const bf16_t* ga = A + (size_t)r0 * lda + c0 * 8;
;   const bf16_t* gb = B + (size_t)r0 * ldb + c0 * 8;
;   const int aoff = (wm * 64 + (lane & 31)) * LDT + (lane >> 5) * 8;
;   const int boff = (wn * 64 + (lane & 31)) * LDT + (lane >> 5) * 8;
;   u32x4 ra0[4], rb0[4], ra1[4], rb1[4];
;   gemm_ldg(ga, gb, lda, ldb, 0, ra0, rb0);
;   gemm_ldg(ga, gb, lda, ldb, 64, ra1, rb1);
;   __syncthreads();
;   gemm_sts(sA, sB, r0, c0, ra0, rb0);
;   __syncthreads();
;   const int nk = K >> 6;
; #pragma unroll 1
;   for (int kt = 0; kt < nk; kt += 2) {
;     if (kt + 2 < nk) gemm_ldg(ga, gb, lda, ldb, (kt + 2) * 64, ra0, rb0);
;     gemm_mma(sA + aoff, sB + boff, acc);
;     gemm_sts(sA + 128 * LDT, sB + 128 * LDT, r0, c0, ra1, rb1);
;     __syncthreads();
;     if (kt + 3 < nk) gemm_ldg(ga, gb, lda, ldb, (kt + 3) * 64, ra1, rb1);
.Lgf3_top:
	s_add_i32 s10, s10, 2
	s_cmp_lt_u32 s10, 14
	s_cselect_b64 s[20:21], -1, 0
	s_cmp_gt_u32 s10, 13
	s_cselect_b64 s[18:19], -1, 0
	s_and_b64 vcc, exec, s[18:19]
	v_lshl_add_u64 v[152:153], v[148:149], 0, v[144:145]
	v_lshl_add_u64 v[150:151], v[146:147], 0, v[144:145]
	s_setprio 1
	ds_read_b128 v[180:183], v155
	ds_read_b128 v[184:187], v156 offset:36864
	ds_read_b128 v[188:191], v155 offset:32
	ds_read_b128 v[192:195], v156 offset:36896
	ds_read_b128 v[196:199], v156 offset:41472
	ds_read_b128 v[200:203], v156 offset:41504
	s_waitcnt lgkmcnt(4)
	v_mfma_f32_32x32x16_bf16 v[50:65], v[180:183], v[184:187], v[50:65]
	v_add_co_u32_e32 v66, vcc, 0x15300000, v152
	s_nop 1
	v_addc_co_u32_e32 v67, vcc, 0, v153, vcc
	v_add_co_u32_e32 v70, vcc, 0xc00000, v150
	global_load_dwordx4 v[66:69], v[66:67], off offset:256
	s_waitcnt lgkmcnt(1)
	v_mfma_f32_32x32x16_bf16 v[34:49], v[180:183], v[196:199], v[34:49]
	s_nop 0
	v_addc_co_u32_e32 v71, vcc, 0, v151, vcc
	v_add_co_u32_e32 v74, vcc, 0x15310000, v152
	global_load_dwordx4 v[70:73], v[70:71], off offset:256
	ds_read_b128 v[180:183], v155 offset:4608
	ds_read_b128 v[204:207], v155 offset:4640
	s_waitcnt lgkmcnt(1)
	v_mfma_f32_32x32x16_bf16 v[18:33], v[180:183], v[184:187], v[18:33]
	s_nop 0
	v_addc_co_u32_e32 v75, vcc, 0, v153, vcc
	v_add_co_u32_e32 v82, vcc, 0xc10000, v150
	global_load_dwordx4 v[74:77], v[74:75], off offset:256
	s_waitcnt lgkmcnt(1)
	v_mfma_f32_32x32x16_bf16 v[2:17], v[180:183], v[196:199], v[2:17]
	s_nop 0
	v_addc_co_u32_e32 v83, vcc, 0, v151, vcc
	v_add_co_u32_e32 v90, vcc, 0x15320000, v152
	global_load_dwordx4 v[82:85], v[82:83], off offset:256
	s_waitcnt lgkmcnt(4)
	v_mfma_f32_32x32x16_bf16 v[50:65], v[188:191], v[192:195], v[50:65]
	s_nop 0
	v_addc_co_u32_e32 v91, vcc, 0, v153, vcc
	v_add_co_u32_e32 v98, vcc, 0xc20000, v150
	global_load_dwordx4 v[90:93], v[90:91], off offset:256
	s_waitcnt lgkmcnt(2)
	v_mfma_f32_32x32x16_bf16 v[34:49], v[188:191], v[200:203], v[34:49]
	s_nop 0
	v_addc_co_u32_e32 v99, vcc, 0, v151, vcc
	v_add_co_u32_e32 v110, vcc, 0x15330000, v152
	global_load_dwordx4 v[98:101], v[98:99], off offset:256
	s_waitcnt lgkmcnt(0)
	v_mfma_f32_32x32x16_bf16 v[18:33], v[204:207], v[192:195], v[18:33]
	s_nop 0
	v_addc_co_u32_e32 v111, vcc, 0, v153, vcc
	v_add_co_u32_e32 v126, vcc, s28, v150
	global_load_dwordx4 v[110:113], v[110:111], off offset:256
	ds_read_b128 v[180:183], v155 offset:64
	ds_read_b128 v[184:187], v156 offset:36928
	ds_read_b128 v[188:191], v155 offset:96
	ds_read_b128 v[192:195], v156 offset:36960
	s_waitcnt lgkmcnt(4)
	v_mfma_f32_32x32x16_bf16 v[2:17], v[204:207], v[200:203], v[2:17]
	s_nop 0
	v_addc_co_u32_e32 v127, vcc, 0, v151, vcc
	global_load_dwordx4 v[126:129], v[126:127], off offset:256
	ds_read_b128 v[196:199], v156 offset:41536
	ds_read_b128 v[200:203], v156 offset:41568
	s_waitcnt lgkmcnt(4)
	v_mfma_f32_32x32x16_bf16 v[50:65], v[180:183], v[184:187], v[50:65]
	s_waitcnt vmcnt(8)
	ds_write_b128 v154, v[78:81] offset:18432
	s_waitcnt lgkmcnt(2)
	v_mfma_f32_32x32x16_bf16 v[34:49], v[180:183], v[196:199], v[34:49]
	ds_write_b128 v154, v[86:89] offset:55296
	ds_read_b128 v[180:183], v155 offset:4672
	ds_read_b128 v[204:207], v155 offset:4704
	s_waitcnt lgkmcnt(1)
	v_mfma_f32_32x32x16_bf16 v[18:33], v[180:183], v[184:187], v[18:33]
	ds_write_b128 v154, v[94:97] offset:23040
	s_waitcnt lgkmcnt(2)
	v_mfma_f32_32x32x16_bf16 v[2:17], v[180:183], v[196:199], v[2:17]
	ds_write_b128 v154, v[102:105] offset:59904
	s_waitcnt lgkmcnt(8)
	v_mfma_f32_32x32x16_bf16 v[50:65], v[188:191], v[192:195], v[50:65]
	ds_write_b128 v154, v[106:109] offset:27648
	s_waitcnt lgkmcnt(7)
	v_mfma_f32_32x32x16_bf16 v[34:49], v[188:191], v[200:203], v[34:49]
	ds_write_b128 v154, v[118:121] offset:64512
	s_waitcnt lgkmcnt(4)
	v_mfma_f32_32x32x16_bf16 v[18:33], v[204:207], v[192:195], v[18:33]
	ds_write_b128 v154, v[114:117] offset:32256
	s_waitcnt lgkmcnt(5)
	v_mfma_f32_32x32x16_bf16 v[2:17], v[204:207], v[200:203], v[2:17]
	ds_write_b128 v157, v[122:125] offset:13824
	s_setprio 0
	s_waitcnt lgkmcnt(0)
	s_barrier
; DI void gemm_ldg(const bf16_t* ga, const bf16_t* gb, int lda, int ldb, int koff, u32x4 (&ra)[4], u32x4 (&rb)[4]) {
; #pragma unroll
;   for (int i = 0; i < 4; ++i) {
;     ra[i] = *(const u32x4*)(ga + (size_t)(32 * i) * lda + koff);
;     rb[i] = *(const u32x4*)(gb + (size_t)(32 * i) * ldb + koff);
;   }
; }
; DI void gemm_sts(bf16_t* dA, bf16_t* dB, int r0, int c0, const u32x4 (&ra)[4], const u32x4 (&rb)[4]) {
; #pragma unroll
;   for (int i = 0; i < 4; ++i) {
;     *(u32x4*)(dA + (r0 + 32 * i) * LDT + c0 * 8) = ra[i];
;     *(u32x4*)(dB + (r0 + 32 * i) * LDT + c0 * 8) = rb[i];
;   }
; }
; DI void gemm_mma(const bf16_t* a_, const bf16_t* b_, f32x16 (&acc)[2][2]) {
;   __builtin_amdgcn_s_setprio(1);
; #pragma unroll
;   for (int kk = 0; kk < 4; ++kk) {
;     bf16x8 a0 = *(const bf16x8*)(a_ + kk * 16);
;     bf16x8 a1 = *(const bf16x8*)(a_ + 32 * LDT + kk * 16);
;     bf16x8 b0 = *(const bf16x8*)(b_ + kk * 16);
;     bf16x8 b1 = *(const bf16x8*)(b_ + 32 * LDT + kk * 16);
;     acc[0][0] = MFMA(a0, b0, acc[0][0]);
;     acc[0][1] = MFMA(a0, b1, acc[0][1]);
;     acc[1][0] = MFMA(a1, b0, acc[1][0]);
;     acc[1][1] = MFMA(a1, b1, acc[1][1]);
;   }
;   __builtin_amdgcn_s_setprio(0);
; }
; DI void gemm_tile(const bf16_t* __restrict__ A, int lda, const bf16_t* __restrict__ B, int ldb, int K,
;                   f32x16 (&acc)[2][2], char* smem) {
;   const int tid = threadIdx.x, lane = tid & 63, w = tid >> 6, wm = w >> 1, wn = w & 1;
;   bf16_t* sA = (bf16_t*)smem;
;   bf16_t* sB = sA + 2 * 128 * LDT;
;   const int r0 = tid >> 3, c0 = tid & 7;
;   const bf16_t* ga = A + (size_t)r0 * lda + c0 * 8;
;   const bf16_t* gb = B + (size_t)r0 * ldb + c0 * 8;
;   const int aoff = (wm * 64 + (lane & 31)) * LDT + (lane >> 5) * 8;
;   const int boff = (wn * 64 + (lane & 31)) * LDT + (lane >> 5) * 8;
;   u32x4 ra0[4], rb0[4], ra1[4], rb1[4];
;   gemm_ldg(ga, gb, lda, ldb, 0, ra0, rb0);
;   gemm_ldg(ga, gb, lda, ldb, 64, ra1, rb1);
;   __syncthreads();
;   gemm_sts(sA, sB, r0, c0, ra0, rb0);
;   __syncthreads();
;   const int nk = K >> 6;
; #pragma unroll 1
;   for (int kt = 0; kt < nk; kt += 2) {
;     if (kt + 2 < nk) gemm_ldg(ga, gb, lda, ldb, (kt + 2) * 64, ra0, rb0);
;     gemm_mma(sA + aoff, sB + boff, acc);
;     gemm_sts(sA + 128 * LDT, sB + 128 * LDT, r0, c0, ra1, rb1);
;     __syncthreads();
;     if (kt + 3 < nk) gemm_ldg(ga, gb, lda, ldb, (kt + 3) * 64, ra1, rb1);
	s_setprio 1
	ds_read_b128 v[208:211], v155 offset:18432
	ds_read_b128 v[180:183], v156 offset:55296
	ds_read_b128 v[184:187], v155 offset:18464
	ds_read_b128 v[188:191], v156 offset:55328
	ds_read_b128 v[192:195], v156 offset:59904
	ds_read_b128 v[196:199], v156 offset:59936
	s_waitcnt lgkmcnt(4)
	v_mfma_f32_32x32x16_bf16 v[50:65], v[208:211], v[180:183], v[50:65]
	v_add_co_u32_e32 v78, vcc, 0x15300000, v152
	s_nop 1
	v_addc_co_u32_e32 v79, vcc, 0, v153, vcc
	v_add_co_u32_e32 v86, vcc, 0xc00000, v150
	global_load_dwordx4 v[78:81], v[78:79], off offset:384
	s_waitcnt lgkmcnt(1)
	v_mfma_f32_32x32x16_bf16 v[34:49], v[208:211], v[192:195], v[34:49]
	s_nop 0
	v_addc_co_u32_e32 v87, vcc, 0, v151, vcc
	v_add_co_u32_e32 v94, vcc, 0x15310000, v152
	global_load_dwordx4 v[86:89], v[86:87], off offset:384
	ds_read_b128 v[208:211], v155 offset:23040
	ds_read_b128 v[200:203], v155 offset:23072
	s_waitcnt lgkmcnt(1)
	v_mfma_f32_32x32x16_bf16 v[18:33], v[208:211], v[180:183], v[18:33]
	s_nop 0
	v_addc_co_u32_e32 v95, vcc, 0, v153, vcc
	v_add_co_u32_e32 v102, vcc, 0xc10000, v150
	global_load_dwordx4 v[94:97], v[94:95], off offset:384
	s_waitcnt lgkmcnt(1)
	v_mfma_f32_32x32x16_bf16 v[2:17], v[208:211], v[192:195], v[2:17]
	s_nop 0
	v_addc_co_u32_e32 v103, vcc, 0, v151, vcc
	v_add_co_u32_e32 v106, vcc, 0x15320000, v152
	global_load_dwordx4 v[102:105], v[102:103], off offset:384
	s_waitcnt lgkmcnt(4)
	v_mfma_f32_32x32x16_bf16 v[50:65], v[184:187], v[188:191], v[50:65]
	s_nop 0
	v_addc_co_u32_e32 v107, vcc, 0, v153, vcc
	v_add_co_u32_e32 v114, vcc, 0xc20000, v150
	global_load_dwordx4 v[106:109], v[106:107], off offset:384
	s_waitcnt lgkmcnt(2)
	v_mfma_f32_32x32x16_bf16 v[34:49], v[184:187], v[196:199], v[34:49]
	s_nop 0
	v_addc_co_u32_e32 v115, vcc, 0, v151, vcc
	global_load_dwordx4 v[118:121], v[114:115], off offset:384
	s_waitcnt lgkmcnt(0)
	v_mfma_f32_32x32x16_bf16 v[18:33], v[200:203], v[188:191], v[18:33]
	v_add_co_u32_e32 v114, vcc, 0x15330000, v152
	s_nop 1
	v_addc_co_u32_e32 v115, vcc, 0, v153, vcc
	v_add_co_u32_e32 v122, vcc, 0xc30000, v150
	global_load_dwordx4 v[114:117], v[114:115], off offset:384
	ds_read_b128 v[208:211], v155 offset:18496
	ds_read_b128 v[180:183], v156 offset:55360
	ds_read_b128 v[184:187], v155 offset:18528
	ds_read_b128 v[188:191], v156 offset:55392
	s_waitcnt lgkmcnt(4)
	v_mfma_f32_32x32x16_bf16 v[2:17], v[200:203], v[196:199], v[2:17]
	s_nop 0
	v_addc_co_u32_e32 v123, vcc, 0, v151, vcc
	global_load_dwordx4 v[122:125], v[122:123], off offset:384
	ds_read_b128 v[192:195], v156 offset:59968
	ds_read_b128 v[196:199], v156 offset:60000
	s_waitcnt lgkmcnt(4)
	v_mfma_f32_32x32x16_bf16 v[50:65], v[208:211], v[180:183], v[50:65]
	s_waitcnt vmcnt(8)
	ds_write_b128 v154, v[66:69]
	s_waitcnt lgkmcnt(2)
	v_mfma_f32_32x32x16_bf16 v[34:49], v[208:211], v[192:195], v[34:49]
	ds_write_b128 v154, v[70:73] offset:36864
	ds_read_b128 v[208:211], v155 offset:23104
	ds_read_b128 v[200:203], v155 offset:23136
	s_waitcnt lgkmcnt(1)
	v_mfma_f32_32x32x16_bf16 v[18:33], v[208:211], v[180:183], v[18:33]
	ds_write_b128 v154, v[74:77] offset:4608
	s_waitcnt lgkmcnt(2)
	v_mfma_f32_32x32x16_bf16 v[2:17], v[208:211], v[192:195], v[2:17]
	ds_write_b128 v154, v[82:85] offset:41472
	s_waitcnt lgkmcnt(8)
	v_mfma_f32_32x32x16_bf16 v[50:65], v[184:187], v[188:191], v[50:65]
	ds_write_b128 v154, v[90:93] offset:9216
	s_waitcnt lgkmcnt(7)
	v_mfma_f32_32x32x16_bf16 v[34:49], v[184:187], v[196:199], v[34:49]
	ds_write_b128 v154, v[98:101] offset:46080
	s_waitcnt lgkmcnt(4)
	v_mfma_f32_32x32x16_bf16 v[18:33], v[200:203], v[188:191], v[18:33]
	ds_write_b128 v154, v[110:113] offset:13824
	s_waitcnt lgkmcnt(5)
	v_mfma_f32_32x32x16_bf16 v[2:17], v[200:203], v[196:199], v[2:17]
	ds_write_b128 v154, v[126:129] offset:50688
	s_setprio 0
	v_lshl_add_u64 v[146:147], v[146:147], 0, s[16:17]
	s_andn2_b64 vcc, exec, s[18:19]
	v_lshl_add_u64 v[148:149], v[148:149], 0, s[16:17]
	s_waitcnt lgkmcnt(0)
	s_barrier
	s_cmp_lt_u32 s10, 12
	s_cbranch_scc1 .Lgf3_top
	s_branch .LBB0_335

; DI void gemm_ldg(const bf16_t* ga, const bf16_t* gb, int lda, int ldb, int koff, u32x4 (&ra)[4], u32x4 (&rb)[4]) {
; #pragma unroll
;   for (int i = 0; i < 4; ++i) {
;     ra[i] = *(const u32x4*)(ga + (size_t)(32 * i) * lda + koff);
;     rb[i] = *(const u32x4*)(gb + (size_t)(32 * i) * ldb + koff);
;   }
; }
; DI void gemm_sts(bf16_t* dA, bf16_t* dB, int r0, int c0, const u32x4 (&ra)[4], const u32x4 (&rb)[4]) {
; #pragma unroll
;   for (int i = 0; i < 4; ++i) {
;     *(u32x4*)(dA + (r0 + 32 * i) * LDT + c0 * 8) = ra[i];
;     *(u32x4*)(dB + (r0 + 32 * i) * LDT + c0 * 8) = rb[i];
;   }
; }
; DI void gemm_mma(const bf16_t* a_, const bf16_t* b_, f32x16 (&acc)[2][2]) {
;   __builtin_amdgcn_s_setprio(1);
; #pragma unroll
;   for (int kk = 0; kk < 4; ++kk) {
;     bf16x8 a0 = *(const bf16x8*)(a_ + kk * 16);
;     bf16x8 a1 = *(const bf16x8*)(a_ + 32 * LDT + kk * 16);
;     bf16x8 b0 = *(const bf16x8*)(b_ + kk * 16);
;     bf16x8 b1 = *(const bf16x8*)(b_ + 32 * LDT + kk * 16);
;     acc[0][0] = MFMA(a0, b0, acc[0][0]);
;     acc[0][1] = MFMA(a0, b1, acc[0][1]);
;     acc[1][0] = MFMA(a1, b0, acc[1][0]);
;     acc[1][1] = MFMA(a1, b1, acc[1][1]);
;   }
;   __builtin_amdgcn_s_setprio(0);
; }
; DI void gemm_tile(const bf16_t* __restrict__ A, int lda, const bf16_t* __restrict__ B, int ldb, int K,
;                   f32x16 (&acc)[2][2], char* smem) {
;   const int tid = threadIdx.x, lane = tid & 63, w = tid >> 6, wm = w >> 1, wn = w & 1;
;   bf16_t* sA = (bf16_t*)smem;
;   bf16_t* sB = sA + 2 * 128 * LDT;
;   const int r0 = tid >> 3, c0 = tid & 7;
;   const bf16_t* ga = A + (size_t)r0 * lda + c0 * 8;
;   const bf16_t* gb = B + (size_t)r0 * ldb + c0 * 8;
;   const int aoff = (wm * 64 + (lane & 31)) * LDT + (lane >> 5) * 8;
;   const int boff = (wn * 64 + (lane & 31)) * LDT + (lane >> 5) * 8;
;   u32x4 ra0[4], rb0[4], ra1[4], rb1[4];
;   gemm_ldg(ga, gb, lda, ldb, 0, ra0, rb0);
;   gemm_ldg(ga, gb, lda, ldb, 64, ra1, rb1);
;   __syncthreads();
;   gemm_sts(sA, sB, r0, c0, ra0, rb0);
;   __syncthreads();
;   const int nk = K >> 6;
; #pragma unroll 1
;   for (int kt = 0; kt < nk; kt += 2) {
;     if (kt + 2 < nk) gemm_ldg(ga, gb, lda, ldb, (kt + 2) * 64, ra0, rb0);
;     gemm_mma(sA + aoff, sB + boff, acc);
;     gemm_sts(sA + 128 * LDT, sB + 128 * LDT, r0, c0, ra1, rb1);
;     __syncthreads();
;     if (kt + 3 < nk) gemm_ldg(ga, gb, lda, ldb, (kt + 3) * 64, ra1, rb1);
.Lgf4_top:
	s_add_i32 s99, s99, 2
	s_cmp_lt_u32 s99, 14
	s_cselect_b64 s[88:89], -1, 0
	s_cmp_gt_u32 s99, 13
	s_cselect_b64 s[86:87], -1, 0
	s_and_b64 vcc, exec, s[86:87]
	v_lshl_add_u64 v[194:195], v[190:191], 0, s[68:69]
	v_lshl_add_u64 v[192:193], v[190:191], 0, s[44:45]
	s_setprio 1
	ds_read_b128 v[232:235], v203
	ds_read_b128 v[236:239], v204 offset:36864
	ds_read_b128 v[240:243], v204 offset:41472
	s_waitcnt lgkmcnt(1)
	v_mfma_f32_32x32x16_bf16 v[50:65], v[232:235], v[236:239], v[50:65]
	v_add_co_u32_e32 v66, vcc, 0x5300000, v194
	s_nop 1
	v_addc_co_u32_e32 v67, vcc, 0, v195, vcc
	v_add_co_u32_e32 v70, vcc, 0xe00000, v192
	s_nop 1
	v_addc_co_u32_e32 v71, vcc, 0, v193, vcc
	v_add_co_u32_e32 v78, vcc, 0x5310000, v194
	global_load_dwordx4 v[66:69], v[66:67], off offset:256
	s_waitcnt lgkmcnt(0)
	v_mfma_f32_32x32x16_bf16 v[34:49], v[232:235], v[240:243], v[34:49]
	s_nop 0
	global_load_dwordx4 v[70:73], v[70:71], off offset:256
	ds_read_b128 v[232:235], v203 offset:4608
	s_waitcnt lgkmcnt(0)
	v_mfma_f32_32x32x16_bf16 v[18:33], v[232:235], v[236:239], v[18:33]
	v_addc_co_u32_e32 v79, vcc, 0, v195, vcc
	v_add_co_u32_e32 v82, vcc, 0xe10000, v192
	s_nop 1
	v_addc_co_u32_e32 v83, vcc, 0, v193, vcc
	v_add_co_u32_e32 v90, vcc, 0x5320000, v194
	global_load_dwordx4 v[78:81], v[78:79], off offset:256
	s_waitcnt lgkmcnt(0)
	v_mfma_f32_32x32x16_bf16 v[2:17], v[232:235], v[240:243], v[2:17]
	s_nop 0
	global_load_dwordx4 v[82:85], v[82:83], off offset:256
	ds_read_b128 v[232:235], v203 offset:32
	ds_read_b128 v[236:239], v204 offset:36896
	ds_read_b128 v[240:243], v204 offset:41504
	s_waitcnt lgkmcnt(1)
	v_mfma_f32_32x32x16_bf16 v[50:65], v[232:235], v[236:239], v[50:65]
	v_addc_co_u32_e32 v91, vcc, 0, v195, vcc
	v_add_co_u32_e32 v94, vcc, 0xe20000, v192
	s_nop 1
	v_addc_co_u32_e32 v95, vcc, 0, v193, vcc
	v_add_co_u32_e32 v110, vcc, 0x5330000, v194
	global_load_dwordx4 v[90:93], v[90:91], off offset:256
	s_waitcnt lgkmcnt(0)
	v_mfma_f32_32x32x16_bf16 v[34:49], v[232:235], v[240:243], v[34:49]
	s_nop 0
	global_load_dwordx4 v[94:97], v[94:95], off offset:256
	ds_read_b128 v[232:235], v203 offset:4640
	s_waitcnt lgkmcnt(0)
	v_mfma_f32_32x32x16_bf16 v[18:33], v[232:235], v[236:239], v[18:33]
	v_addc_co_u32_e32 v111, vcc, 0, v195, vcc
	v_add_co_u32_e32 v118, vcc, s90, v192
	s_nop 1
	v_addc_co_u32_e32 v119, vcc, 0, v193, vcc
	global_load_dwordx4 v[110:113], v[110:111], off offset:256
	s_waitcnt lgkmcnt(0)
	v_mfma_f32_32x32x16_bf16 v[2:17], v[232:235], v[240:243], v[2:17]
	s_nop 0
	global_load_dwordx4 v[118:121], v[118:119], off offset:256
	ds_read_b128 v[232:235], v203 offset:64
	ds_read_b128 v[236:239], v204 offset:36928
	ds_read_b128 v[240:243], v204 offset:41536
	s_waitcnt lgkmcnt(1)
	v_mfma_f32_32x32x16_bf16 v[50:65], v[232:235], v[236:239], v[50:65]
	s_waitcnt vmcnt(8)
	ds_write_b128 v202, v[74:77] offset:18432
	s_waitcnt lgkmcnt(1)
	v_mfma_f32_32x32x16_bf16 v[34:49], v[232:235], v[240:243], v[34:49]
	ds_write_b128 v202, v[106:109] offset:55296
	ds_read_b128 v[232:235], v203 offset:4672
	s_waitcnt lgkmcnt(0)
	v_mfma_f32_32x32x16_bf16 v[18:33], v[232:235], v[236:239], v[18:33]
	ds_write_b128 v202, v[86:89] offset:23040
	s_waitcnt lgkmcnt(1)
	v_mfma_f32_32x32x16_bf16 v[2:17], v[232:235], v[240:243], v[2:17]
	ds_write_b128 v202, v[114:117] offset:59904
	ds_read_b128 v[232:235], v203 offset:96
	ds_read_b128 v[236:239], v204 offset:36960
	ds_read_b128 v[240:243], v204 offset:41568
	s_waitcnt lgkmcnt(1)
	v_mfma_f32_32x32x16_bf16 v[50:65], v[232:235], v[236:239], v[50:65]
	ds_write_b128 v202, v[98:101] offset:27648
	s_waitcnt lgkmcnt(1)
	v_mfma_f32_32x32x16_bf16 v[34:49], v[232:235], v[240:243], v[34:49]
	ds_write_b128 v202, v[122:125] offset:64512
	ds_read_b128 v[232:235], v203 offset:4704
	s_waitcnt lgkmcnt(0)
	v_mfma_f32_32x32x16_bf16 v[18:33], v[232:235], v[236:239], v[18:33]
	ds_write_b128 v202, v[102:105] offset:32256
	s_waitcnt lgkmcnt(1)
	v_mfma_f32_32x32x16_bf16 v[2:17], v[232:235], v[240:243], v[2:17]
	ds_write_b128 v205, v[126:129] offset:13824
	s_setprio 0
	s_waitcnt lgkmcnt(0)
	s_barrier
; DI void gemm_ldg(const bf16_t* ga, const bf16_t* gb, int lda, int ldb, int koff, u32x4 (&ra)[4], u32x4 (&rb)[4]) {
; #pragma unroll
;   for (int i = 0; i < 4; ++i) {
;     ra[i] = *(const u32x4*)(ga + (size_t)(32 * i) * lda + koff);
;     rb[i] = *(const u32x4*)(gb + (size_t)(32 * i) * ldb + koff);
;   }
; }
; DI void gemm_sts(bf16_t* dA, bf16_t* dB, int r0, int c0, const u32x4 (&ra)[4], const u32x4 (&rb)[4]) {
; #pragma unroll
;   for (int i = 0; i < 4; ++i) {
;     *(u32x4*)(dA + (r0 + 32 * i) * LDT + c0 * 8) = ra[i];
;     *(u32x4*)(dB + (r0 + 32 * i) * LDT + c0 * 8) = rb[i];
;   }
; }
; DI void gemm_mma(const bf16_t* a_, const bf16_t* b_, f32x16 (&acc)[2][2]) {
;   __builtin_amdgcn_s_setprio(1);
; #pragma unroll
;   for (int kk = 0; kk < 4; ++kk) {
;     bf16x8 a0 = *(const bf16x8*)(a_ + kk * 16);
;     bf16x8 a1 = *(const bf16x8*)(a_ + 32 * LDT + kk * 16);
;     bf16x8 b0 = *(const bf16x8*)(b_ + kk * 16);
;     bf16x8 b1 = *(const bf16x8*)(b_ + 32 * LDT + kk * 16);
;     acc[0][0] = MFMA(a0, b0, acc[0][0]);
;     acc[0][1] = MFMA(a0, b1, acc[0][1]);
;     acc[1][0] = MFMA(a1, b0, acc[1][0]);
;     acc[1][1] = MFMA(a1, b1, acc[1][1]);
;   }
;   __builtin_amdgcn_s_setprio(0);
; }
; DI void gemm_tile(const bf16_t* __restrict__ A, int lda, const bf16_t* __restrict__ B, int ldb, int K,
;                   f32x16 (&acc)[2][2], char* smem) {
;   const int tid = threadIdx.x, lane = tid & 63, w = tid >> 6, wm = w >> 1, wn = w & 1;
;   bf16_t* sA = (bf16_t*)smem;
;   bf16_t* sB = sA + 2 * 128 * LDT;
;   const int r0 = tid >> 3, c0 = tid & 7;
;   const bf16_t* ga = A + (size_t)r0 * lda + c0 * 8;
;   const bf16_t* gb = B + (size_t)r0 * ldb + c0 * 8;
;   const int aoff = (wm * 64 + (lane & 31)) * LDT + (lane >> 5) * 8;
;   const int boff = (wn * 64 + (lane & 31)) * LDT + (lane >> 5) * 8;
;   u32x4 ra0[4], rb0[4], ra1[4], rb1[4];
;   gemm_ldg(ga, gb, lda, ldb, 0, ra0, rb0);
;   gemm_ldg(ga, gb, lda, ldb, 64, ra1, rb1);
;   __syncthreads();
;   gemm_sts(sA, sB, r0, c0, ra0, rb0);
;   __syncthreads();
;   const int nk = K >> 6;
; #pragma unroll 1
;   for (int kt = 0; kt < nk; kt += 2) {
;     if (kt + 2 < nk) gemm_ldg(ga, gb, lda, ldb, (kt + 2) * 64, ra0, rb0);
;     gemm_mma(sA + aoff, sB + boff, acc);
;     gemm_sts(sA + 128 * LDT, sB + 128 * LDT, r0, c0, ra1, rb1);
;     __syncthreads();
;     if (kt + 3 < nk) gemm_ldg(ga, gb, lda, ldb, (kt + 3) * 64, ra1, rb1);
	s_setprio 1
	ds_read_b128 v[244:247], v203 offset:18432
	ds_read_b128 v[232:235], v204 offset:55296
	ds_read_b128 v[236:239], v204 offset:59904
	s_waitcnt lgkmcnt(1)
	v_mfma_f32_32x32x16_bf16 v[50:65], v[244:247], v[232:235], v[50:65]
	v_add_co_u32_e32 v74, vcc, 0x5300000, v194
	s_nop 1
	v_addc_co_u32_e32 v75, vcc, 0, v195, vcc
	v_add_co_u32_e32 v86, vcc, 0xe00000, v192
	s_nop 1
	v_addc_co_u32_e32 v87, vcc, 0, v193, vcc
	global_load_dwordx4 v[74:77], v[74:75], off offset:384
	s_waitcnt lgkmcnt(0)
	v_mfma_f32_32x32x16_bf16 v[34:49], v[244:247], v[236:239], v[34:49]
	s_nop 0
	global_load_dwordx4 v[106:109], v[86:87], off offset:384
	ds_read_b128 v[244:247], v203 offset:23040
	s_waitcnt lgkmcnt(0)
	v_mfma_f32_32x32x16_bf16 v[18:33], v[244:247], v[232:235], v[18:33]
	v_add_co_u32_e32 v86, vcc, 0x5310000, v194
	s_nop 1
	v_addc_co_u32_e32 v87, vcc, 0, v195, vcc
	v_add_co_u32_e32 v98, vcc, 0xe10000, v192
	s_nop 1
	v_addc_co_u32_e32 v99, vcc, 0, v193, vcc
	global_load_dwordx4 v[86:89], v[86:87], off offset:384
	s_waitcnt lgkmcnt(0)
	v_mfma_f32_32x32x16_bf16 v[2:17], v[244:247], v[236:239], v[2:17]
	s_nop 0
	global_load_dwordx4 v[114:117], v[98:99], off offset:384
	ds_read_b128 v[244:247], v203 offset:18464
	ds_read_b128 v[232:235], v204 offset:55328
	ds_read_b128 v[236:239], v204 offset:59936
	s_waitcnt lgkmcnt(1)
	v_mfma_f32_32x32x16_bf16 v[50:65], v[244:247], v[232:235], v[50:65]
	v_add_co_u32_e32 v98, vcc, 0x5320000, v194
	s_nop 1
	v_addc_co_u32_e32 v99, vcc, 0, v195, vcc
	v_add_co_u32_e32 v102, vcc, 0xe20000, v192
	s_nop 1
	v_addc_co_u32_e32 v103, vcc, 0, v193, vcc
	global_load_dwordx4 v[98:101], v[98:99], off offset:384
	s_waitcnt lgkmcnt(0)
	v_mfma_f32_32x32x16_bf16 v[34:49], v[244:247], v[236:239], v[34:49]
	s_nop 0
	global_load_dwordx4 v[122:125], v[102:103], off offset:384
	ds_read_b128 v[244:247], v203 offset:23072
	s_waitcnt lgkmcnt(0)
	v_mfma_f32_32x32x16_bf16 v[18:33], v[244:247], v[232:235], v[18:33]
	v_add_co_u32_e32 v102, vcc, 0x5330000, v194
	s_nop 1
	v_addc_co_u32_e32 v103, vcc, 0, v195, vcc
	v_add_co_u32_e32 v126, vcc, 0xe30000, v192
	s_nop 1
	v_addc_co_u32_e32 v127, vcc, 0, v193, vcc
	global_load_dwordx4 v[102:105], v[102:103], off offset:384
	s_waitcnt lgkmcnt(0)
	v_mfma_f32_32x32x16_bf16 v[2:17], v[244:247], v[236:239], v[2:17]
	s_nop 0
	global_load_dwordx4 v[126:129], v[126:127], off offset:384
	ds_read_b128 v[244:247], v203 offset:18496
	ds_read_b128 v[232:235], v204 offset:55360
	ds_read_b128 v[236:239], v204 offset:59968
	s_waitcnt lgkmcnt(1)
	v_mfma_f32_32x32x16_bf16 v[50:65], v[244:247], v[232:235], v[50:65]
	s_waitcnt vmcnt(8)
	ds_write_b128 v202, v[66:69]
	s_waitcnt lgkmcnt(1)
	v_mfma_f32_32x32x16_bf16 v[34:49], v[244:247], v[236:239], v[34:49]
	ds_write_b128 v202, v[70:73] offset:36864
	ds_read_b128 v[244:247], v203 offset:23104
	s_waitcnt lgkmcnt(0)
	v_mfma_f32_32x32x16_bf16 v[18:33], v[244:247], v[232:235], v[18:33]
	ds_write_b128 v202, v[78:81] offset:4608
	s_waitcnt lgkmcnt(1)
	v_mfma_f32_32x32x16_bf16 v[2:17], v[244:247], v[236:239], v[2:17]
	ds_write_b128 v202, v[82:85] offset:41472
	ds_read_b128 v[244:247], v203 offset:18528
	ds_read_b128 v[232:235], v204 offset:55392
	ds_read_b128 v[236:239], v204 offset:60000
	s_waitcnt lgkmcnt(1)
	v_mfma_f32_32x32x16_bf16 v[50:65], v[244:247], v[232:235], v[50:65]
	ds_write_b128 v202, v[90:93] offset:9216
	s_waitcnt lgkmcnt(1)
	v_mfma_f32_32x32x16_bf16 v[34:49], v[244:247], v[236:239], v[34:49]
	ds_write_b128 v202, v[94:97] offset:46080
	ds_read_b128 v[244:247], v203 offset:23136
	s_waitcnt lgkmcnt(0)
	v_mfma_f32_32x32x16_bf16 v[18:33], v[244:247], v[232:235], v[18:33]
	ds_write_b128 v202, v[110:113] offset:13824
	s_waitcnt lgkmcnt(1)
	v_mfma_f32_32x32x16_bf16 v[2:17], v[244:247], v[236:239], v[2:17]
	ds_write_b128 v202, v[118:121] offset:50688
	s_setprio 0
	s_andn2_b64 vcc, exec, s[86:87]
	v_lshl_add_u64 v[190:191], v[190:191], 0, s[64:65]
	s_waitcnt lgkmcnt(0)
	s_barrier
	s_cmp_lt_u32 s99, 12
	s_cbranch_scc1 .Lgf4_top
	s_branch .LBB0_462
